# barrier-2 gap: CUs owning a sample-conv unit touch its 30 conv-state rows (input data) into L2 while the barrier completes
# speedup vs baseline: 1.0004x; 1.0004x over previous
; __global__ void __launch_bounds__(NTHR, 2) hybrid_fwd(Args args) {
;     ...
;     { const XbState xs = xcd_barrier_arrive(bar);
;       unsigned ln = threadIdx.x & 63u; asm volatile("" : "+v"(ln)); const unsigned wv = threadIdx.x >> 6;
;       const unsigned p = 192u * wv + 2u * ln, q = 192u * wv + 128u + ln; const float* w = args.in[14]; const float* bb = args.in[15];
; #pragma unroll
;       for (int j = 0; j < CW; ++j) { cw.wp[j] = ldg<f32x2>(w + (size_t)j * DCONV, p * 4u); cw.wq[j] = ldg<float>(w + (size_t)j * DCONV, q * 4u); }
;       cw.bp = ldg<f32x2>(bb, p * 4u); cw.bq = ldg<float>(bb, q * 4u);
;       xcd_barrier_wait(bar, xs); }
.LBB0_382:
	s_or_b64 exec, exec, s[4:5]
	s_and_b32 s4, s2, 7
	s_lshl_b32 s4, s4, 5
	s_lshr_b32 s5, s2, 3
	s_add_i32 s4, s4, s5
	s_bitcmp1_b32 s4, 1
	s_cbranch_scc1 .Lsc_notouch
	s_load_dwordx2 s[10:11], s[0:1], 0x30
	s_and_b32 s5, s4, 1
	s_lshr_b32 s4, s4, 2
	s_lshl_b32 s4, s4, 1
	s_or_b32 s4, s4, s5
	s_mul_i32 s4, s4, 0x2d000
	v_lshlrev_b32_e32 v250, 7, v0
	v_add_u32_e32 v252, 0x10000, v250
	s_waitcnt lgkmcnt(0)
	s_add_u32 s10, s10, s4
	s_addc_u32 s11, s11, 0
	global_load_dword v251, v250, s[10:11]
	global_load_dword v251, v252, s[10:11]
	v_add_u32_e32 v252, 0x20000, v250
	v_cmp_gt_u32_e32 vcc, 0x2d000, v252
	s_and_saveexec_b64 s[4:5], vcc
	global_load_dword v251, v252, s[10:11]
	s_or_b64 exec, exec, s[4:5]
.Lsc_notouch:
	s_add_u32 s10, s24, 0x1800
	s_waitcnt lgkmcnt(0)
	v_and_b32_e32 v1, 63, v0
	v_lshrrev_b32_e32 v5, 6, v0
	s_movk_i32 s4, 0xc0
	s_addc_u32 s11, s25, 0
	s_nop 0
	v_mad_u32_u24 v4, v5, s4, v1
	s_add_u32 s4, s24, 0x3000
	s_addc_u32 s5, s25, 0
	s_add_u32 s16, s24, 0x4800
	s_addc_u32 s17, s25, 0
	s_add_u32 s18, s24, 0x6000
	s_addc_u32 s19, s25, 0
	s_add_u32 s22, s24, 0x7800
	s_addc_u32 s23, s25, 0
	s_add_u32 s20, s24, 0x9000
	s_addc_u32 s21, s25, 0
	s_add_u32 s12, s24, 0xa800
	s_addc_u32 s13, s25, 0
	s_add_u32 s34, s24, 0xc000
	s_addc_u32 s35, s25, 0
	s_add_u32 s36, s24, 0xd800
	s_addc_u32 s37, s25, 0
	s_add_u32 s38, s24, 0xf000
	s_addc_u32 s39, s25, 0
	s_add_u32 s40, s24, 0x10800
	s_addc_u32 s41, s25, 0
	s_add_u32 s42, s24, 0x12000
	s_addc_u32 s43, s25, 0
	s_add_u32 s44, s24, 0x13800
	s_addc_u32 s45, s25, 0
	v_mul_u32_u24_e32 v5, 0x300, v5
	s_add_u32 s46, s24, 0x15000
	v_lshl_add_u32 v1, v1, 3, v5
	v_mov_b32_e32 v5, 0x200
	s_addc_u32 s47, s25, 0
	v_lshl_add_u32 v4, v4, 2, v5
	global_load_dwordx2 v[58:59], v1, s[16:17]
	global_load_dwordx2 v[60:61], v1, s[18:19]
	global_load_dwordx2 v[62:63], v1, s[22:23]
	global_load_dwordx2 v[64:65], v1, s[20:21]
	global_load_dwordx2 v[66:67], v1, s[12:13]
	global_load_dwordx2 v[68:69], v1, s[34:35]
	global_load_dwordx2 v[70:71], v1, s[36:37]
	global_load_dwordx2 v[72:73], v1, s[38:39]
	global_load_dwordx2 v[74:75], v1, s[40:41]
	global_load_dwordx2 v[76:77], v1, s[42:43]
	global_load_dwordx2 v[78:79], v1, s[44:45]
	global_load_dwordx2 v[80:81], v1, s[46:47]
	global_load_dword v166, v4, s[12:13]
	global_load_dword v167, v4, s[34:35]
	global_load_dword v168, v4, s[36:37]
	global_load_dword v169, v4, s[38:39]
	global_load_dword v170, v4, s[40:41]
	global_load_dword v171, v4, s[42:43]
	global_load_dword v172, v4, s[44:45]
	global_load_dword v173, v4, s[46:47]
	s_add_u32 s12, s24, 0x16800
	s_addc_u32 s13, s25, 0
	s_add_u32 s34, s24, 0x18000
	s_addc_u32 s35, s25, 0
	s_add_u32 s36, s24, 0x19800
	s_addc_u32 s37, s25, 0
	s_add_u32 s38, s24, 0x1b000
	s_addc_u32 s39, s25, 0
	s_add_u32 s40, s24, 0x1c800
	s_addc_u32 s41, s25, 0
	s_add_u32 s42, s24, 0x1e000
	s_addc_u32 s43, s25, 0
	s_add_u32 s44, s24, 0x1f800
	s_addc_u32 s45, s25, 0
	s_add_u32 s46, s24, 0x21000
	s_addc_u32 s47, s25, 0
	global_load_dwordx2 v[82:83], v1, s[12:13]
	global_load_dwordx2 v[84:85], v1, s[34:35]
	global_load_dwordx2 v[86:87], v1, s[36:37]
	global_load_dwordx2 v[88:89], v1, s[38:39]
	global_load_dwordx2 v[90:91], v1, s[40:41]
	global_load_dwordx2 v[92:93], v1, s[42:43]
	global_load_dwordx2 v[94:95], v1, s[44:45]
	global_load_dwordx2 v[96:97], v1, s[46:47]
	global_load_dword v174, v4, s[12:13]
	global_load_dword v175, v4, s[34:35]
	global_load_dword v176, v4, s[36:37]
	global_load_dword v177, v4, s[38:39]
	global_load_dword v178, v4, s[40:41]
	global_load_dword v179, v4, s[42:43]
	global_load_dword v180, v4, s[44:45]
	global_load_dword v181, v4, s[46:47]
	s_add_u32 s12, s24, 0x22800
	s_addc_u32 s13, s25, 0
	s_add_u32 s34, s24, 0x24000
	s_addc_u32 s35, s25, 0
	s_add_u32 s36, s24, 0x25800
	s_addc_u32 s37, s25, 0
	s_add_u32 s38, s24, 0x27000
	s_addc_u32 s39, s25, 0
	s_add_u32 s40, s24, 0x28800
	s_addc_u32 s41, s25, 0
	s_add_u32 s42, s24, 0x2a000
	s_addc_u32 s43, s25, 0
	s_add_u32 s44, s24, 0x2b800
	s_addc_u32 s45, s25, 0
	s_add_u32 s46, s24, 0x2d000
	global_load_dwordx2 v[98:99], v1, s[12:13]
	global_load_dwordx2 v[100:101], v1, s[34:35]
	global_load_dwordx2 v[102:103], v1, s[36:37]
	global_load_dwordx2 v[104:105], v1, s[38:39]
	s_addc_u32 s47, s25, 0
	global_load_dwordx2 v[106:107], v1, s[40:41]
	global_load_dwordx2 v[108:109], v1, s[42:43]
	global_load_dwordx2 v[110:111], v1, s[44:45]
	global_load_dwordx2 v[112:113], v1, s[46:47]
	global_load_dword v182, v4, s[12:13]
	global_load_dword v183, v4, s[34:35]
	global_load_dword v184, v4, s[36:37]
	global_load_dword v185, v4, s[38:39]
	global_load_dword v186, v4, s[40:41]
	global_load_dword v187, v4, s[42:43]
	global_load_dword v188, v4, s[44:45]
	global_load_dword v189, v4, s[46:47]
	global_load_dwordx2 v[114:115], v1, s[24:25]
	global_load_dwordx2 v[116:117], v1, s[10:11]
	global_load_dwordx2 v[118:119], v1, s[4:5]
	global_load_dwordx2 v[120:121], v1, s[26:27]
	global_load_dword v190, v4, s[24:25]
	global_load_dword v191, v4, s[10:11]
	global_load_dword v192, v4, s[4:5]
	global_load_dword v193, v4, s[16:17]
	global_load_dword v194, v4, s[18:19]
	global_load_dword v195, v4, s[22:23]
	global_load_dword v196, v4, s[20:21]
	global_load_dword v197, v4, s[26:27]
	s_and_saveexec_b64 s[4:5], s[14:15]
	s_cbranch_execz .LBB0_412
	v_mov_b32_e32 v1, 0x7000
	s_mov_b32 s16, 0
